# LRU: staging LDS writes moved behind conv-weight loads; pass 1 prefetches both directions gate weights/bias/lambda at item start
# speedup vs baseline: 1.0085x; 1.0018x over previous
; #define LAS __attribute__((address_space(3)))
; template <bool PASS2>
; __device__ __forceinline__ void lru_item(const Frame& F, const Args& a, int item) {
;     ...
;     for (int idx = F.tid; idx < 259 * 16; idx += 512) { const int row = idx >> 4, ch = idx & 15; const int t = t0 - 1 + row; u32x4 v = (u32x4){0u, 0u, 0u, 0u};
;         if (t >= 0 && t < SEQ) v = *(const u32x4*)(proj + (rowbase + t) * NIN + C_XB + n * 128 + 8 * ch);
;         *(LAS u32x4*)(R0 + row * AT_PITCH + 16 * ch) = v; }
.LBB0_143:
	s_mul_hi_i32 s4, s55, 0x2aaaaaab
	s_ashr_i32 s5, s4, 1
	s_lshr_b32 s6, s4, 31
	s_add_i32 s5, s5, s6
	s_mul_i32 s7, s5, 12
	s_sub_i32 s13, s55, s7
	s_ashr_i32 s7, s5, 31
	s_lshr_b32 s7, s7, 28
	s_add_i32 s7, s5, s7
	s_and_b32 s7, s7, -16
	s_ashr_i32 s4, s4, 5
	s_sub_i32 s56, s5, s7
	s_add_i32 s38, s4, s6
	s_lshl_b32 s57, s56, 8
	s_ashr_i32 s39, s38, 31
	s_lshl_b32 s4, s13, 7
	s_lshl_b64 s[6:7], s[38:39], 12
	s_ashr_i32 s5, s4, 31
	v_add_u32_e32 v8, s57, v112
	s_mov_b64 s[8:9], 0
	v_mov_b32_e32 v9, v114
	v_mov_b32_e32 v10, v113
	s_waitcnt vmcnt(0)
	s_barrier
	v_cmp_gt_u32_e64 s[8:9], 48, v144
	v_add_u32_e32 v9, 0x100, v8
	v_mov_b32_e32 v226, 0
	v_mov_b32_e32 v227, 0
	v_mov_b32_e32 v228, 0
	v_mov_b32_e32 v229, 0
	v_cmp_gt_u32_e32 vcc, s46, v9
	s_and_b64 vcc, vcc, s[8:9]
	s_and_saveexec_b64 s[10:11], vcc
	s_cbranch_execz .Lstg_p1a_8
	v_or_b32_e32 v6, s6, v9
	v_mov_b64_e32 v[4:5], s[22:23]
	v_mad_u64_u32 v[4:5], s[14:15], v6, s47, v[4:5]
	v_mad_i32_i24 v5, s7, v118, v5
	v_lshl_add_u64 v[4:5], s[4:5], 1, v[4:5]
	v_lshl_add_u64 v[4:5], v[4:5], 0, v[94:95]
	v_add_co_u32_e32 v4, vcc, 0xe402000, v4
	s_nop 1
	v_addc_co_u32_e32 v5, vcc, 0, v5, vcc
	global_load_dwordx4 v[226:229], v[4:5], off offset:1024
.Lstg_p1a_8:
	s_or_b64 exec, exec, s[10:11]
	v_mov_b32_e32 v194, 0
	v_mov_b32_e32 v195, 0
	v_mov_b32_e32 v196, 0
	v_mov_b32_e32 v197, 0
	v_cmp_gt_u32_e32 vcc, s46, v8
	s_and_saveexec_b64 s[10:11], vcc
	s_cbranch_execz .Lstg_p1a_0
	v_or_b32_e32 v6, s6, v8
	v_mov_b64_e32 v[4:5], s[22:23]
	v_mad_u64_u32 v[4:5], s[14:15], v6, s47, v[4:5]
	v_mad_i32_i24 v5, s7, v118, v5
	v_lshl_add_u64 v[4:5], s[4:5], 1, v[4:5]
	v_lshl_add_u64 v[4:5], v[4:5], 0, v[94:95]
	v_add_co_u32_e32 v4, vcc, 0xe402000, v4
	s_nop 1
	v_addc_co_u32_e32 v5, vcc, 0, v5, vcc
	global_load_dwordx4 v[194:197], v[4:5], off offset:1024
.Lstg_p1a_0:
	s_or_b64 exec, exec, s[10:11]
	v_add_u32_e32 v8, 32, v8
	v_mov_b32_e32 v198, 0
	v_mov_b32_e32 v199, 0
	v_mov_b32_e32 v200, 0
	v_mov_b32_e32 v201, 0
	v_cmp_gt_u32_e32 vcc, s46, v8
	s_and_saveexec_b64 s[10:11], vcc
	v_or_b32_e32 v6, s6, v8
	v_mov_b64_e32 v[4:5], s[22:23]
	v_mad_u64_u32 v[4:5], s[14:15], v6, s47, v[4:5]
	v_mad_i32_i24 v5, s7, v118, v5
	v_lshl_add_u64 v[4:5], s[4:5], 1, v[4:5]
	v_lshl_add_u64 v[4:5], v[4:5], 0, v[94:95]
	v_add_co_u32_e32 v4, vcc, 0xe402000, v4
	s_nop 1
	v_addc_co_u32_e32 v5, vcc, 0, v5, vcc
	global_load_dwordx4 v[198:201], v[4:5], off offset:1024
	s_or_b64 exec, exec, s[10:11]
	v_add_u32_e32 v8, 32, v8
	v_mov_b32_e32 v202, 0
	v_mov_b32_e32 v203, 0
	v_mov_b32_e32 v204, 0
	v_mov_b32_e32 v205, 0
	v_cmp_gt_u32_e32 vcc, s46, v8
	s_and_saveexec_b64 s[10:11], vcc
	v_or_b32_e32 v6, s6, v8
	v_mov_b64_e32 v[4:5], s[22:23]
	v_mad_u64_u32 v[4:5], s[14:15], v6, s47, v[4:5]
	v_mad_i32_i24 v5, s7, v118, v5
	v_lshl_add_u64 v[4:5], s[4:5], 1, v[4:5]
	v_lshl_add_u64 v[4:5], v[4:5], 0, v[94:95]
	v_add_co_u32_e32 v4, vcc, 0xe402000, v4
	s_nop 1
	v_addc_co_u32_e32 v5, vcc, 0, v5, vcc
	global_load_dwordx4 v[202:205], v[4:5], off offset:1024
	s_or_b64 exec, exec, s[10:11]
	v_add_u32_e32 v8, 32, v8
	v_mov_b32_e32 v206, 0
	v_mov_b32_e32 v207, 0
	v_mov_b32_e32 v208, 0
	v_mov_b32_e32 v209, 0
	v_cmp_gt_u32_e32 vcc, s46, v8
	s_and_saveexec_b64 s[10:11], vcc
	v_or_b32_e32 v6, s6, v8
	v_mov_b64_e32 v[4:5], s[22:23]
	v_mad_u64_u32 v[4:5], s[14:15], v6, s47, v[4:5]
	v_mad_i32_i24 v5, s7, v118, v5
	v_lshl_add_u64 v[4:5], s[4:5], 1, v[4:5]
	v_lshl_add_u64 v[4:5], v[4:5], 0, v[94:95]
	v_add_co_u32_e32 v4, vcc, 0xe402000, v4
	s_nop 1
	v_addc_co_u32_e32 v5, vcc, 0, v5, vcc
	global_load_dwordx4 v[206:209], v[4:5], off offset:1024
	s_or_b64 exec, exec, s[10:11]
	v_add_u32_e32 v8, 32, v8
	v_mov_b32_e32 v210, 0
	v_mov_b32_e32 v211, 0
	v_mov_b32_e32 v212, 0
	v_mov_b32_e32 v213, 0
	v_cmp_gt_u32_e32 vcc, s46, v8
	s_and_saveexec_b64 s[10:11], vcc
	v_or_b32_e32 v6, s6, v8
	v_mov_b64_e32 v[4:5], s[22:23]
	v_mad_u64_u32 v[4:5], s[14:15], v6, s47, v[4:5]
	v_mad_i32_i24 v5, s7, v118, v5
	v_lshl_add_u64 v[4:5], s[4:5], 1, v[4:5]
	v_lshl_add_u64 v[4:5], v[4:5], 0, v[94:95]
	v_add_co_u32_e32 v4, vcc, 0xe402000, v4
	s_nop 1
	v_addc_co_u32_e32 v5, vcc, 0, v5, vcc
	global_load_dwordx4 v[210:213], v[4:5], off offset:1024
	s_or_b64 exec, exec, s[10:11]
	v_add_u32_e32 v8, 32, v8
	v_mov_b32_e32 v214, 0
	v_mov_b32_e32 v215, 0
	v_mov_b32_e32 v216, 0
	v_mov_b32_e32 v217, 0
	v_cmp_gt_u32_e32 vcc, s46, v8
	s_and_saveexec_b64 s[10:11], vcc
	v_or_b32_e32 v6, s6, v8
	v_mov_b64_e32 v[4:5], s[22:23]
	v_mad_u64_u32 v[4:5], s[14:15], v6, s47, v[4:5]
	v_mad_i32_i24 v5, s7, v118, v5
	v_lshl_add_u64 v[4:5], s[4:5], 1, v[4:5]
	v_lshl_add_u64 v[4:5], v[4:5], 0, v[94:95]
	v_add_co_u32_e32 v4, vcc, 0xe402000, v4
	s_nop 1
	v_addc_co_u32_e32 v5, vcc, 0, v5, vcc
	global_load_dwordx4 v[214:217], v[4:5], off offset:1024
	s_or_b64 exec, exec, s[10:11]
	v_add_u32_e32 v8, 32, v8
	v_mov_b32_e32 v218, 0
	v_mov_b32_e32 v219, 0
	v_mov_b32_e32 v220, 0
	v_mov_b32_e32 v221, 0
	v_cmp_gt_u32_e32 vcc, s46, v8
	s_and_saveexec_b64 s[10:11], vcc
	v_or_b32_e32 v6, s6, v8
	v_mov_b64_e32 v[4:5], s[22:23]
	v_mad_u64_u32 v[4:5], s[14:15], v6, s47, v[4:5]
	v_mad_i32_i24 v5, s7, v118, v5
	v_lshl_add_u64 v[4:5], s[4:5], 1, v[4:5]
	v_lshl_add_u64 v[4:5], v[4:5], 0, v[94:95]
	v_add_co_u32_e32 v4, vcc, 0xe402000, v4
	s_nop 1
	v_addc_co_u32_e32 v5, vcc, 0, v5, vcc
	global_load_dwordx4 v[218:221], v[4:5], off offset:1024
	s_or_b64 exec, exec, s[10:11]
	v_add_u32_e32 v8, 32, v8
	v_mov_b32_e32 v222, 0
	v_mov_b32_e32 v223, 0
	v_mov_b32_e32 v224, 0
	v_mov_b32_e32 v225, 0
	v_cmp_gt_u32_e32 vcc, s46, v8
	s_and_saveexec_b64 s[10:11], vcc
	v_or_b32_e32 v6, s6, v8
	v_mov_b64_e32 v[4:5], s[22:23]
	v_mad_u64_u32 v[4:5], s[14:15], v6, s47, v[4:5]
; #define LAS __attribute__((address_space(3)))
; template <bool PASS2>
; __device__ __forceinline__ void lru_item(const Frame& F, const Args& a, int item) {
;     ...
;     for (int idx = F.tid; idx < 259 * 16; idx += 512) { const int row = idx >> 4, ch = idx & 15; const int t = t0 - 1 + row; u32x4 v = (u32x4){0u, 0u, 0u, 0u};
;         if (t >= 0 && t < SEQ) v = *(const u32x4*)(proj + (rowbase + t) * NIN + C_XB + n * 128 + 8 * ch);
;         *(LAS u32x4*)(R0 + row * AT_PITCH + 16 * ch) = v; }
;     {
;         f32x4 cw[4][2], cbv[2];
; #pragma unroll
;         for (int j = 0; j < 4; ++j) { cw[j][0] = *(const f32x4*)(a.conv_w + j * 1536 + n * 128 + 8 * cch); cw[j][1] = *(const f32x4*)(a.conv_w + j * 1536 + n * 128 + 8 * cch + 4); }
;         cbv[0] = *(const f32x4*)(a.conv_b + n * 128 + 8 * cch); cbv[1] = *(const f32x4*)(a.conv_b + n * 128 + 8 * cch + 4);
;         u32x4 ybv[8];
;         if (PASS2) {
; #pragma unroll
;             for (int it = 0; it < 8; ++it) ybv[it] = *(const u32x4*)(proj + (rowbase + t0 + r0 + 32 * it) * NIN + C_YB + n * 128 + 8 * cch);
;         }
;         __syncthreads();
;     ...
;         const bf16_t* wt = (const bf16_t*)(a.ws + WS_WLRU) + (size_t)((dir * 12 + n) * 2) * 16384 + (size_t)c * 128 + 8 * fq;
;         bf16x8 wrf[4], wif[4];
; #pragma unroll
;         for (int ks = 0; ks < 4; ++ks) { wrf[ks] = *(const bf16x8*)(wt + 32 * ks); wif[ks] = *(const bf16x8*)(wt + 16384 + 32 * ks); }
;         const float ba = a.lru_ba[dir * 1536 + cg_], bi = a.lru_bi[dir * 1536 + cg_];
;         const float lam = a.lru_lambda[dir * 1536 + cg_];
	v_mad_i32_i24 v5, s7, v118, v5
	v_lshl_add_u64 v[4:5], s[4:5], 1, v[4:5]
	v_lshl_add_u64 v[4:5], v[4:5], 0, v[94:95]
	v_add_co_u32_e32 v4, vcc, 0xe402000, v4
	s_nop 1
	v_addc_co_u32_e32 v5, vcc, 0, v5, vcc
	global_load_dwordx4 v[222:225], v[4:5], off offset:1024
	s_or_b64 exec, exec, s[10:11]
	s_lshl_b64 s[6:7], s[4:5], 2
	v_lshl_add_u64 v[16:17], v[96:97], 0, s[6:7]
	v_add_co_u32_e32 v4, vcc, 0x1000, v16
	v_lshl_add_u64 v[8:9], v[16:17], 0, s[30:31]
	s_nop 0
	v_addc_co_u32_e32 v5, vcc, 0, v17, vcc
	v_add_co_u32_e32 v14, vcc, 0x3000, v16
	v_lshl_add_u64 v[12:13], v[16:17], 0, s[34:35]
	s_nop 0
	v_addc_co_u32_e32 v15, vcc, 0, v17, vcc
	global_load_dwordx4 v[36:39], v[16:17], off
	global_load_dwordx4 v[32:35], v[16:17], off offset:16
	s_nop 0
	global_load_dwordx4 v[4:7], v[4:5], off offset:2048
	s_nop 0
	global_load_dwordx4 v[8:11], v[8:9], off offset:16
	s_nop 0
	global_load_dwordx4 v[46:49], v[14:15], off
	global_load_dwordx4 v[40:43], v[12:13], off offset:16
	v_lshl_add_u64 v[12:13], v[16:17], 0, s[36:37]
	v_add_co_u32_e32 v16, vcc, 0x4000, v16
	global_load_dwordx4 v[12:15], v[12:13], off offset:16
	s_nop 0
	v_addc_co_u32_e32 v17, vcc, 0, v17, vcc
	global_load_dwordx4 v[16:19], v[16:17], off offset:2048
	v_lshl_add_u64 v[24:25], v[98:99], 0, s[6:7]
	global_load_dwordx4 v[20:23], v[24:25], off
	s_nop 0
	global_load_dwordx4 v[24:27], v[24:25], off offset:16
	s_mov_b32 s5, 0
	v_mov_b32_e32 v44, v115
	v_mov_b32_e32 v45, v108
	v_readlane_b32 s98, v242, 17
	v_readlane_b32 s99, v242, 18
	v_add_u32_e32 v248, s4, v92
	v_ashrrev_i32_e32 v249, 31, v248
	v_lshlrev_b64 v[248:249], 2, v[248:249]
	s_nop 1
	v_lshl_add_u64 v[250:251], s[98:99], 0, v[248:249]
	global_load_dword v178, v[250:251], off
	s_add_u32 s98, s98, 0x1800
	s_addc_u32 s99, s99, 0
	v_lshl_add_u64 v[250:251], s[98:99], 0, v[248:249]
	global_load_dword v142, v[250:251], off
	s_lshl_b32 s100, s13, 16
	s_mov_b32 s101, 0
	v_lshl_add_u64 v[250:251], v[102:103], 0, s[100:101]
	global_load_dwordx4 v[146:149], v[250:251], off
	global_load_dwordx4 v[150:153], v[250:251], off offset:64
	global_load_dwordx4 v[154:157], v[250:251], off offset:128
	global_load_dwordx4 v[158:161], v[250:251], off offset:192
	v_lshl_add_u64 v[252:253], s[86:87], 0, v[248:249]
	v_lshl_add_u64 v[254:255], s[90:91], 0, v[248:249]
	global_load_dword v179, v[252:253], off
	global_load_dword v180, v[254:255], off
	s_add_u32 s100, s100, 0x8000
	v_lshl_add_u64 v[250:251], v[102:103], 0, s[100:101]
	global_load_dwordx4 v[162:165], v[250:251], off
	global_load_dwordx4 v[166:169], v[250:251], off offset:64
	global_load_dwordx4 v[170:173], v[250:251], off offset:128
	global_load_dwordx4 v[174:177], v[250:251], off offset:192
	s_add_u32 s100, s100, 0xb8000
	v_lshl_add_u64 v[250:251], v[102:103], 0, s[100:101]
	global_load_dwordx4 v[182:185], v[250:251], off
	global_load_dwordx4 v[186:189], v[250:251], off offset:64
	global_load_dwordx4 v[230:233], v[250:251], off offset:128
	global_load_dwordx4 v[234:237], v[250:251], off offset:192
	s_add_u32 s98, s86, 0x1800
	s_addc_u32 s99, s87, 0
	v_lshl_add_u64 v[252:253], s[98:99], 0, v[248:249]
	s_add_u32 s98, s90, 0x1800
	s_addc_u32 s99, s91, 0
	v_lshl_add_u64 v[254:255], s[98:99], 0, v[248:249]
	global_load_dword v143, v[252:253], off
	global_load_dword v145, v[254:255], off
	s_add_u32 s100, s100, 0x8000
	v_lshl_add_u64 v[250:251], v[102:103], 0, s[100:101]
	global_load_dwordx4 v[238:241], v[250:251], off
	global_load_dwordx4 v[134:137], v[250:251], off offset:64
	global_load_dwordx4 v[138:141], v[250:251], off offset:128
	global_load_dwordx4 v[244:247], v[250:251], off offset:192
	v_cmp_gt_u32_e64 s[98:99], 48, v144
	v_add_u32_e32 v243, 0x2200, v113
	s_waitcnt vmcnt(38)
	s_and_saveexec_b64 s[100:101], s[98:99]
	s_cbranch_execz .Lstg_p1a_w8
	ds_write_b128 v243, v[226:229] offset:60928
.Lstg_p1a_w8:
	s_or_b64 exec, exec, s[100:101]
	ds_write_b128 v113, v[194:197]
	ds_write_b128 v113, v[198:201] offset:8704
	s_waitcnt vmcnt(37)
	ds_write_b128 v113, v[202:205] offset:17408
	s_waitcnt vmcnt(36)
	ds_write_b128 v113, v[206:209] offset:26112
	s_waitcnt vmcnt(35)
	ds_write_b128 v113, v[210:213] offset:34816
	s_waitcnt vmcnt(34)
	ds_write_b128 v113, v[214:217] offset:43520
	s_waitcnt vmcnt(33)
	ds_write_b128 v113, v[218:221] offset:52224
	s_waitcnt vmcnt(32)
	ds_write_b128 v113, v[222:225] offset:60928
	s_waitcnt lgkmcnt(0)
	s_barrier
	s_waitcnt vmcnt(8)
	v_mov_b32_e32 v28, v34
	v_mov_b32_e32 v30, v32
	v_mov_b32_e32 v32, v38
	v_mov_b32_e32 v34, v36
	s_waitcnt vmcnt(6)
	v_mov_b32_e32 v29, v10
	v_mov_b32_e32 v10, v35
	v_mov_b32_e32 v31, v8
	v_mov_b32_e32 v8, v33
	v_mov_b32_e32 v33, v6
	v_mov_b32_e32 v6, v39
	v_mov_b32_e32 v35, v4
	v_mov_b32_e32 v4, v37
	s_waitcnt vmcnt(4)
	v_mov_b32_e32 v36, v42
	v_mov_b32_e32 v38, v40
	v_mov_b32_e32 v40, v48
	v_mov_b32_e32 v42, v46
	s_waitcnt vmcnt(3)
	v_mov_b32_e32 v37, v14
	v_mov_b32_e32 v14, v43
	v_mov_b32_e32 v39, v12
	v_mov_b32_e32 v12, v41
	s_waitcnt vmcnt(2)
	v_mov_b32_e32 v41, v18
	v_mov_b32_e32 v18, v49
	v_mov_b32_e32 v43, v16
	v_mov_b32_e32 v16, v47
; #define LAS __attribute__((address_space(3)))
; __device__ __forceinline__ unsigned cvt_pk_bf16(float lo, float hi) { unsigned r; asm volatile("v_cvt_pk_bf16_f32 %0, %1, %2" : "=v"(r) : "v"(lo), "v"(hi)); return r; }
; __device__ __forceinline__ float bflo(unsigned w) { return __uint_as_float(w << 16); }
; __device__ __forceinline__ float bfhi(unsigned w) { return __uint_as_float(w & 0xffff0000u); }
; __device__ __forceinline__ int lru_perm(int t) { return (t & ~63) | ((t & 12) << 2) | ((t & 48) >> 2) | (t & 3); }
; template <bool PASS2>
; __device__ __forceinline__ void lru_item(const Frame& F, const Args& a, int item) {
;     ...
;         for (int it = 0; it < 8; ++it) { const int tl = r0 + 32 * it;
;             f32x4 x0 = cbv[0], x1 = cbv[1];
; #pragma unroll
;             for (int j = 0; j < 4; ++j) { const u32x4 v = *(const LAS u32x4*)(R0 + (tl + j) * AT_PITCH + 16 * cch);
;                 x0[0] += cw[j][0][0] * bflo(v.x); x0[1] += cw[j][0][1] * bfhi(v.x); x0[2] += cw[j][0][2] * bflo(v.y); x0[3] += cw[j][0][3] * bfhi(v.y);
;                 x1[0] += cw[j][1][0] * bflo(v.z); x1[1] += cw[j][1][1] * bfhi(v.z); x1[2] += cw[j][1][2] * bflo(v.w); x1[3] += cw[j][1][3] * bfhi(v.w); }
;             u32x4 o; o.x = cvt_pk_bf16(x0[0], x0[1]); o.y = cvt_pk_bf16(x0[2], x0[3]); o.z = cvt_pk_bf16(x1[0], x1[1]); o.w = cvt_pk_bf16(x1[2], x1[3]);
;             *(LAS u32x4*)(AT + lru_perm(tl) * AT_PITCH + 16 * cch) = o; }
.LBB0_148:
	v_add_u32_e32 v84, s5, v113
	ds_read_b128 v[46:49], v84
	ds_read_b128 v[50:53], v84 offset:272
	ds_read_b128 v[54:57], v84 offset:544
	ds_read_b128 v[58:61], v84 offset:816
	v_and_or_b32 v62, v45, s49, v111
	v_add_u32_e32 v64, 32, v45
	v_mad_u64_u32 v[62:63], s[6:7], v62, s45, v[100:101]
	v_and_b32_e32 v65, 12, v44
	v_and_b32_e32 v63, 0xfffffc3, v64
	s_waitcnt lgkmcnt(2)
	v_lshlrev_b32_e32 v67, 16, v50
	v_lshlrev_b32_e32 v66, 16, v46
	v_and_b32_e32 v69, 0xffff0000, v50
	v_and_b32_e32 v68, 0xffff0000, v46
	v_or3_b32 v63, v63, v65, v109
	v_lshlrev_b32_e32 v71, 16, v51
	v_lshlrev_b32_e32 v70, 16, v47
	v_and_b32_e32 v51, 0xffff0000, v51
	v_and_b32_e32 v50, 0xffff0000, v47
	v_lshlrev_b32_e32 v47, 16, v52
	v_lshlrev_b32_e32 v46, 16, v48
	v_and_b32_e32 v73, 0xffff0000, v52
	v_and_b32_e32 v72, 0xffff0000, v48
	v_lshlrev_b32_e32 v75, 16, v53
	v_lshlrev_b32_e32 v74, 16, v49
	v_and_b32_e32 v53, 0xffff0000, v53
	v_and_b32_e32 v52, 0xffff0000, v49
	s_waitcnt lgkmcnt(0)
	v_lshlrev_b32_e32 v49, 16, v58
	v_lshlrev_b32_e32 v48, 16, v54
	v_and_b32_e32 v77, 0xffff0000, v58
	v_and_b32_e32 v76, 0xffff0000, v54
	v_lshlrev_b32_e32 v78, 16, v55
	v_and_b32_e32 v58, 0xffff0000, v55
	v_lshlrev_b32_e32 v55, 16, v60
	v_lshlrev_b32_e32 v54, 16, v56
	v_and_b32_e32 v81, 0xffff0000, v60
	v_and_b32_e32 v80, 0xffff0000, v56
	v_lshlrev_b32_e32 v82, 16, v57
	v_and_b32_e32 v60, 0xffff0000, v57
	v_pk_mul_f32 v[56:57], v[34:35], v[66:67]
	v_pk_mul_f32 v[66:67], v[4:5], v[68:69]
	v_mad_u64_u32 v[64:65], s[6:7], v63, s45, v[100:101]
	v_pk_mul_f32 v[68:69], v[32:33], v[70:71]
	v_pk_mul_f32 v[50:51], v[6:7], v[50:51]
	v_pk_mul_f32 v[46:47], v[30:31], v[46:47]
	v_pk_mul_f32 v[70:71], v[8:9], v[72:73]
	v_pk_mul_f32 v[72:73], v[28:29], v[74:75]
	v_pk_mul_f32 v[52:53], v[10:11], v[52:53]
	s_waitcnt vmcnt(1)
	v_add_f32_e32 v56, v20, v56
	v_add_f32_e32 v63, v21, v66
	v_lshlrev_b32_e32 v79, 16, v59
	v_and_b32_e32 v59, 0xffff0000, v59
	v_lshlrev_b32_e32 v83, 16, v61
	v_and_b32_e32 v61, 0xffff0000, v61
	v_pk_mul_f32 v[48:49], v[42:43], v[48:49]
	v_pk_mul_f32 v[74:75], v[16:17], v[76:77]
	v_add_f32_e32 v65, v22, v68
	v_add_f32_e32 v50, v23, v50
	s_waitcnt vmcnt(0)
	v_add_f32_e32 v46, v24, v46
	v_add_f32_e32 v66, v25, v70
	v_add_f32_e32 v68, v26, v72
	v_add_f32_e32 v52, v27, v52
	v_add_f32_e32 v56, v56, v57
	v_add_f32_e32 v57, v63, v67
	v_pk_mul_f32 v[76:77], v[40:41], v[78:79]
	v_pk_mul_f32 v[58:59], v[18:19], v[58:59]
	v_pk_mul_f32 v[54:55], v[38:39], v[54:55]
	v_pk_mul_f32 v[78:79], v[12:13], v[80:81]
	v_pk_mul_f32 v[80:81], v[36:37], v[82:83]
	v_pk_mul_f32 v[60:61], v[14:15], v[60:61]
	v_add_f32_e32 v63, v65, v69
	v_add_f32_e32 v50, v50, v51
	v_add_f32_e32 v46, v46, v47
	v_add_f32_e32 v47, v66, v71
	v_add_f32_e32 v51, v68, v73
	v_add_f32_e32 v52, v52, v53
	v_add_f32_e32 v48, v56, v48
	v_add_f32_e32 v53, v57, v74
	v_add_f32_e32 v56, v63, v76
	v_add_f32_e32 v50, v50, v58
	v_add_f32_e32 v46, v46, v54
	v_add_f32_e32 v47, v47, v78
	v_add_f32_e32 v51, v51, v80
	v_add_f32_e32 v52, v52, v60
	v_add_f32_e32 v48, v48, v49
	v_add_f32_e32 v49, v53, v75
	v_add_f32_e32 v53, v56, v77
	v_add_f32_e32 v50, v50, v59
	v_add_f32_e32 v54, v46, v55
	v_add_f32_e32 v55, v47, v79
	v_add_f32_e32 v51, v51, v81
	v_add_f32_e32 v52, v52, v61
	v_cvt_pk_bf16_f32 v46, v48, v49
	v_cvt_pk_bf16_f32 v47, v53, v50
	v_cvt_pk_bf16_f32 v48, v54, v55
	v_cvt_pk_bf16_f32 v49, v51, v52
	ds_write_b128 v62, v[46:49]
	ds_read_b128 v[46:49], v84 offset:8976
	ds_read_b128 v[50:53], v84 offset:8704
	ds_read_b128 v[54:57], v84 offset:9248
	ds_read_b128 v[58:61], v84 offset:9520
	s_addk_i32 s5, 0x4400
	s_waitcnt lgkmcnt(3)
	v_lshlrev_b32_e32 v63, 16, v46
	s_waitcnt lgkmcnt(2)
	v_lshlrev_b32_e32 v62, 16, v50
	v_and_b32_e32 v67, 0xffff0000, v46
	v_and_b32_e32 v66, 0xffff0000, v50
	v_lshlrev_b32_e32 v69, 16, v47
	v_lshlrev_b32_e32 v68, 16, v51
	v_and_b32_e32 v47, 0xffff0000, v47
	v_and_b32_e32 v46, 0xffff0000, v51
	v_lshlrev_b32_e32 v51, 16, v48
	v_lshlrev_b32_e32 v50, 16, v52
	v_and_b32_e32 v71, 0xffff0000, v48
	v_and_b32_e32 v70, 0xffff0000, v52
	v_lshlrev_b32_e32 v73, 16, v49
	v_lshlrev_b32_e32 v72, 16, v53
	v_and_b32_e32 v49, 0xffff0000, v49
	v_and_b32_e32 v48, 0xffff0000, v53
	s_waitcnt lgkmcnt(0)
	v_lshlrev_b32_e32 v53, 16, v58
	v_lshlrev_b32_e32 v52, 16, v54
	v_and_b32_e32 v75, 0xffff0000, v58
	v_and_b32_e32 v74, 0xffff0000, v54
	v_lshlrev_b32_e32 v76, 16, v55
	v_and_b32_e32 v58, 0xffff0000, v55
	v_lshlrev_b32_e32 v55, 16, v60
	v_lshlrev_b32_e32 v54, 16, v56
	v_and_b32_e32 v79, 0xffff0000, v60
	v_and_b32_e32 v78, 0xffff0000, v56
	v_lshlrev_b32_e32 v80, 16, v57
	v_and_b32_e32 v60, 0xffff0000, v57
	v_pk_mul_f32 v[56:57], v[34:35], v[62:63]
	v_pk_mul_f32 v[62:63], v[4:5], v[66:67]
	v_pk_mul_f32 v[66:67], v[32:33], v[68:69]
	v_pk_mul_f32 v[46:47], v[6:7], v[46:47]
	v_pk_mul_f32 v[50:51], v[30:31], v[50:51]
	v_pk_mul_f32 v[68:69], v[8:9], v[70:71]
	v_pk_mul_f32 v[70:71], v[28:29], v[72:73]
	v_pk_mul_f32 v[48:49], v[10:11], v[48:49]
	v_add_f32_e32 v56, v20, v56
	v_lshlrev_b32_e32 v77, 16, v59
	v_and_b32_e32 v59, 0xffff0000, v59
	v_lshlrev_b32_e32 v81, 16, v61
	v_and_b32_e32 v61, 0xffff0000, v61
	v_pk_mul_f32 v[52:53], v[42:43], v[52:53]
	v_add_f32_e32 v62, v21, v62
	v_add_f32_e32 v65, v22, v66
	v_add_f32_e32 v46, v23, v46
	v_add_f32_e32 v50, v24, v50
	v_add_f32_e32 v66, v25, v68
	v_add_f32_e32 v68, v26, v70
	v_add_f32_e32 v48, v27, v48
	v_add_f32_e32 v56, v56, v57
	v_pk_mul_f32 v[72:73], v[16:17], v[74:75]
	v_pk_mul_f32 v[74:75], v[40:41], v[76:77]
	v_pk_mul_f32 v[58:59], v[18:19], v[58:59]
	v_pk_mul_f32 v[54:55], v[38:39], v[54:55]
	v_pk_mul_f32 v[76:77], v[12:13], v[78:79]
	v_pk_mul_f32 v[78:79], v[36:37], v[80:81]
	v_pk_mul_f32 v[60:61], v[14:15], v[60:61]
	v_add_f32_e32 v57, v62, v63
	v_add_f32_e32 v62, v65, v67
	v_add_f32_e32 v46, v46, v47
	v_add_f32_e32 v47, v50, v51
	v_add_f32_e32 v50, v66, v69
	v_add_f32_e32 v51, v68, v71
	v_add_f32_e32 v48, v48, v49
	v_add_f32_e32 v49, v56, v52
	v_add_u32_e32 v45, 64, v45
	v_add_u32_e32 v44, 16, v44
	s_cmp_eq_u32 s5, 0x11000
	v_add_f32_e32 v52, v57, v72
	v_add_f32_e32 v56, v62, v74
	v_add_f32_e32 v46, v46, v58
	v_add_f32_e32 v47, v47, v54
	v_add_f32_e32 v50, v50, v76
	v_add_f32_e32 v51, v51, v78
	v_add_f32_e32 v48, v48, v60
	v_add_f32_e32 v49, v49, v53
	v_add_f32_e32 v52, v52, v73
	v_add_f32_e32 v53, v56, v75
	v_add_f32_e32 v54, v46, v59
	v_add_f32_e32 v55, v47, v55
	v_add_f32_e32 v50, v50, v77
	v_add_f32_e32 v51, v51, v79
	v_add_f32_e32 v56, v48, v61
	v_cvt_pk_bf16_f32 v46, v49, v52
	v_cvt_pk_bf16_f32 v47, v53, v54
	v_cvt_pk_bf16_f32 v48, v55, v50
	v_cvt_pk_bf16_f32 v49, v51, v56
	ds_write_b128 v64, v[46:49]
	s_cbranch_scc0 .LBB0_148
; template <bool PASS2>
; __device__ __forceinline__ void lru_item(const Frame& F, const Args& a, int item) {
;     ...
;         const bf16_t* wt = (const bf16_t*)(a.ws + WS_WLRU) + (size_t)((dir * 12 + n) * 2) * 16384 + (size_t)c * 128 + 8 * fq;
;         bf16x8 wrf[4], wif[4];
; #pragma unroll
;         for (int ks = 0; ks < 4; ++ks) { wrf[ks] = *(const bf16x8*)(wt + 32 * ks); wif[ks] = *(const bf16x8*)(wt + 16384 + 32 * ks); }
;         const float ba = a.lru_ba[dir * 1536 + cg_], bi = a.lru_bi[dir * 1536 + cg_];
;         const float lam = a.lru_lambda[dir * 1536 + cg_];
;         const float logu = -8.0f * log1pf(__expf(-lam));
	v_add_u32_e32 v104, s4, v92
	v_ashrrev_i32_e32 v105, 31, v104
	v_readlane_b32 s60, v242, 17
	v_lshlrev_b64 v[4:5], 2, v[104:105]
	v_readlane_b32 s61, v242, 18
	s_waitcnt lgkmcnt(0)
	s_barrier
	v_lshl_add_u64 v[6:7], s[60:61], 0, v[4:5]
	s_waitcnt vmcnt(0)
	v_mov_b32_e32 v26, v178
	s_lshl_b32 s40, s13, 1
	s_ashr_i32 s41, s40, 31
	s_lshl_b64 s[4:5], s[40:41], 15
	v_lshl_add_u64 v[20:21], v[102:103], 0, s[4:5]
	v_lshl_add_u64 v[22:23], s[86:87], 0, v[4:5]
	v_lshl_add_u64 v[24:25], s[90:91], 0, v[4:5]
	v_add_co_u32_e32 v32, vcc, 0x8000, v20
	v_mov_b32_e32 v4, v146
	v_mov_b32_e32 v5, v147
	v_mov_b32_e32 v6, v148
	v_mov_b32_e32 v7, v149
	v_mov_b32_e32 v8, v150
	v_mov_b32_e32 v9, v151
	v_mov_b32_e32 v10, v152
	v_mov_b32_e32 v11, v153
	v_mov_b32_e32 v12, v154
	v_mov_b32_e32 v13, v155
	v_mov_b32_e32 v14, v156
	v_mov_b32_e32 v15, v157
	v_mov_b32_e32 v16, v158
	v_mov_b32_e32 v17, v159
	v_mov_b32_e32 v18, v160
	v_mov_b32_e32 v19, v161
	v_mov_b32_e32 v128, v179
	v_mov_b32_e32 v130, v180
	v_addc_co_u32_e32 v33, vcc, 0, v21, vcc
	s_mov_b32 s39, 0
	v_mov_b32_e32 v106, 1.0
	v_or_b32_e32 v124, 64, v122
	v_or_b32_e32 v125, 0x80, v122
	v_or_b32_e32 v126, 0xc0, v122
	v_add_u32_e32 v127, s57, v93
	v_mov_b32_e32 v129, 0
	v_mov_b32_e32 v132, v116
	v_readlane_b32 s62, v242, 19
	v_readlane_b32 s63, v242, 20
	v_readlane_b32 s64, v242, 21
	v_readlane_b32 s65, v242, 22
	v_readlane_b32 s66, v242, 23
	v_readlane_b32 s67, v242, 24
	v_readlane_b32 s68, v242, 25
	v_readlane_b32 s69, v242, 26
	v_readlane_b32 s70, v242, 27
	v_readlane_b32 s71, v242, 28
	v_readlane_b32 s72, v242, 29
	v_readlane_b32 s73, v242, 30
	v_readlane_b32 s74, v242, 31
	v_readlane_b32 s75, v242, 32
	s_waitcnt vmcnt(6)
	v_mul_f32_e32 v20, 0xbfb8aa3b, v26
	v_exp_f32_e32 v38, v20
	v_mov_b32_e32 v20, v162
	v_mov_b32_e32 v21, v163
	v_mov_b32_e32 v22, v164
	v_mov_b32_e32 v23, v165
	v_mov_b32_e32 v24, v166
	v_mov_b32_e32 v25, v167
	v_mov_b32_e32 v26, v168
	v_mov_b32_e32 v27, v169
	v_mov_b32_e32 v28, v170
	v_mov_b32_e32 v29, v171
	v_mov_b32_e32 v30, v172
	v_mov_b32_e32 v31, v173
	s_nop 0
	v_mov_b32_e32 v32, v174
	v_mov_b32_e32 v33, v175
	v_mov_b32_e32 v34, v176
	v_mov_b32_e32 v35, v177
	v_add_f32_e32 v39, 1.0, v38
	v_add_f32_e32 v40, -1.0, v39
	v_frexp_mant_f32_e32 v41, v39
	v_cvt_f64_f32_e32 v[36:37], v39
	v_sub_f32_e32 v42, v40, v39
	v_frexp_exp_i32_f64_e32 v36, v[36:37]
	v_cmp_gt_f32_e32 vcc, s50, v41
	v_sub_f32_e32 v40, v38, v40
	v_add_f32_e32 v37, 1.0, v42
	v_subbrev_co_u32_e32 v36, vcc, 0, v36, vcc
	v_add_f32_e32 v37, v40, v37
	v_sub_u32_e32 v40, 0, v36
	v_cvt_f32_i32_e32 v36, v36
	v_ldexp_f32 v39, v39, v40
	v_ldexp_f32 v37, v37, v40
	v_add_f32_e32 v40, -1.0, v39
	v_add_f32_e32 v41, 1.0, v39
	v_add_f32_e32 v42, 1.0, v40
	v_add_f32_e32 v43, -1.0, v41
	v_sub_f32_e32 v42, v39, v42
	v_sub_f32_e32 v39, v39, v43
	v_mul_f32_e32 v43, 0x3f317218, v36
	v_add_f32_e32 v42, v37, v42
	v_add_f32_e32 v37, v37, v39
	v_fma_f32 v39, v36, s51, -v43
	v_add_f32_e32 v44, v40, v42
	v_add_f32_e32 v45, v41, v37
	v_fmac_f32_e32 v39, 0xb102e308, v36
	v_sub_f32_e32 v36, v44, v40
	v_sub_f32_e32 v40, v45, v41
	v_rcp_f32_e32 v41, v45
	v_add_f32_e32 v46, v43, v39
	v_sub_f32_e32 v37, v37, v40
	v_sub_f32_e32 v40, v46, v43
	v_sub_f32_e32 v39, v39, v40
	v_mul_f32_e32 v40, v44, v41
	v_sub_f32_e32 v36, v42, v36
	v_mul_f32_e32 v42, v45, v40
	v_fma_f32 v43, v40, v45, -v42
	v_fmac_f32_e32 v43, v40, v37
	v_add_f32_e32 v47, v42, v43
	v_sub_f32_e32 v48, v44, v47
	v_sub_f32_e32 v42, v47, v42
	v_sub_f32_e32 v44, v44, v48
	v_sub_f32_e32 v42, v42, v43
	v_sub_f32_e32 v43, v44, v47
	v_add_f32_e32 v36, v36, v43
	v_add_f32_e32 v36, v42, v36
	v_add_f32_e32 v42, v48, v36
	v_mul_f32_e32 v43, v41, v42
	v_sub_f32_e32 v44, v48, v42
	v_mul_f32_e32 v47, v45, v43
	v_add_f32_e32 v36, v36, v44
	v_add_f32_e32 v44, v40, v43
	v_fma_f32 v45, v43, v45, -v47
	v_sub_f32_e32 v40, v44, v40
	v_fmac_f32_e32 v45, v43, v37
	v_sub_f32_e32 v37, v43, v40
	v_add_f32_e32 v40, v47, v45
	v_sub_f32_e32 v43, v40, v47
	v_sub_f32_e32 v47, v42, v40
	v_sub_f32_e32 v42, v42, v47
	v_sub_f32_e32 v40, v42, v40
	v_sub_f32_e32 v43, v43, v45
	v_add_f32_e32 v36, v36, v40
	v_add_f32_e32 v36, v43, v36
	v_add_f32_e32 v36, v47, v36
	v_mul_f32_e32 v36, v41, v36
	v_add_f32_e32 v36, v37, v36
	v_add_f32_e32 v37, v44, v36
	v_mul_f32_e32 v40, v37, v37
	v_fmamk_f32 v43, v40, 0x3e9b6dac, v117
	v_sub_f32_e32 v41, v37, v44
	v_ldexp_f32 v42, v37, 1
	v_mul_f32_e32 v37, v37, v40
	v_fmaak_f32 v40, v40, v43, 0x3f2aaada
	v_mul_f32_e32 v37, v37, v40
	v_add_f32_e32 v40, v42, v37
	v_sub_f32_e32 v36, v36, v41
	v_sub_f32_e32 v41, v40, v42
	v_ldexp_f32 v36, v36, 1
	v_sub_f32_e32 v37, v37, v41
	v_add_f32_e32 v36, v36, v37
	v_add_f32_e32 v37, v40, v36
	v_sub_f32_e32 v40, v37, v40
	v_add_f32_e32 v41, v46, v37
	v_sub_f32_e32 v36, v36, v40
	v_sub_f32_e32 v40, v41, v46
	v_sub_f32_e32 v42, v41, v40
	v_sub_f32_e32 v37, v37, v40
	v_add_f32_e32 v40, v39, v36
	v_sub_f32_e32 v42, v46, v42
	v_sub_f32_e32 v43, v40, v39
	v_add_f32_e32 v37, v37, v42
	v_sub_f32_e32 v42, v40, v43
	v_sub_f32_e32 v36, v36, v43
	v_sub_f32_e32 v39, v39, v42
	v_add_f32_e32 v37, v40, v37
	v_add_f32_e32 v36, v36, v39
	v_add_f32_e32 v39, v41, v37
	v_sub_f32_e32 v40, v39, v41
	v_sub_f32_e32 v37, v37, v40
	v_add_f32_e32 v36, v36, v37
	v_add_f32_e32 v36, v39, v36
	v_cmp_neq_f32_e32 vcc, s52, v38
	s_nop 1
	v_cndmask_b32_e32 v36, v119, v36, vcc
	v_cmp_ngt_f32_e32 vcc, -1.0, v38
	s_nop 1
	v_cndmask_b32_e32 v36, v120, v36, vcc
	v_cmp_neq_f32_e32 vcc, -1.0, v38
	s_nop 1
	v_cndmask_b32_e32 v36, v121, v36, vcc
	v_cmp_lt_f32_e64 vcc, |v38|, s53
	s_nop 1
	v_cndmask_b32_e32 v36, v36, v38, vcc
	v_mul_f32_e32 v131, 0xc1000000, v36

; template <bool PASS2>
; __device__ __forceinline__ void lru_item(const Frame& F, const Args& a, int item) {
;     ...
;         const bf16_t* wt = (const bf16_t*)(a.ws + WS_WLRU) + (size_t)((dir * 12 + n) * 2) * 16384 + (size_t)c * 128 + 8 * fq;
;         bf16x8 wrf[4], wif[4];
; #pragma unroll
;         for (int ks = 0; ks < 4; ++ks) { wrf[ks] = *(const bf16x8*)(wt + 32 * ks); wif[ks] = *(const bf16x8*)(wt + 16384 + 32 * ks); }
;         const float ba = a.lru_ba[dir * 1536 + cg_], bi = a.lru_bi[dir * 1536 + cg_];
;         const float lam = a.lru_lambda[dir * 1536 + cg_];
;         const float logu = -8.0f * log1pf(__expf(-lam));
;         float hc = 0.f, TA = 1.f, TB = 0.f;
;         if (PASS2) { const f32x2* ag = (const f32x2*)(a.ws + WS_AGG) + ((size_t)(b * NCHUNK) * 2 + dir) * 1536 + cg_;
;             f32x2 pa[NCHUNK];
; #pragma unroll
;             for (int cc = 0; cc < NCHUNK; ++cc) pa[cc] = ag[(size_t)cc * 2 * 1536];
; #pragma unroll
;             for (int i = 0; i < NCHUNK; ++i) { const int cc = dir ? NCHUNK - 1 - i : i; const bool use = dir ? (cc > chunk) : (cc < chunk); if (use) hc = pa[cc].x * hc + pa[cc].y; } }
;         const int tstart = dir ? SEQ - 1 : 0;
;         if (dir == 1) __syncthreads();
.LBB0_186:
	s_or_b64 exec, exec, s[14:15]
	v_add_u32_e32 v4, 0x600, v104
	v_mov_b32_e32 v5, v95
	v_readlane_b32 s60, v242, 17
	v_lshlrev_b64 v[4:5], 2, v[4:5]
	v_readlane_b32 s61, v242, 18
	s_add_i32 s14, s40, 24
	s_mov_b32 s15, s12
	v_lshl_add_u64 v[6:7], s[60:61], 0, v[4:5]
	v_mov_b32_e32 v36, v142
	s_lshl_b64 s[14:15], s[14:15], 15
	v_lshl_add_u64 v[20:21], v[102:103], 0, s[14:15]
	v_lshl_add_u64 v[22:23], s[86:87], 0, v[4:5]
	v_lshl_add_u64 v[24:25], s[90:91], 0, v[4:5]
	v_add_co_u32_e32 v32, vcc, 0x8000, v20
	v_mov_b32_e32 v4, v182
	v_mov_b32_e32 v5, v183
	v_mov_b32_e32 v6, v184
	v_mov_b32_e32 v7, v185
	v_mov_b32_e32 v8, v186
	v_mov_b32_e32 v9, v187
	v_mov_b32_e32 v10, v188
	v_mov_b32_e32 v11, v189
	v_mov_b32_e32 v12, v230
	v_mov_b32_e32 v13, v231
	v_mov_b32_e32 v14, v232
	v_mov_b32_e32 v15, v233
	v_mov_b32_e32 v16, v234
	v_mov_b32_e32 v17, v235
	v_mov_b32_e32 v18, v236
	v_mov_b32_e32 v19, v237
	v_mov_b32_e32 v128, v143
	v_mov_b32_e32 v129, v145
	v_addc_co_u32_e32 v33, vcc, 0, v21, vcc
	v_mov_b32_e32 v20, v238
	v_mov_b32_e32 v21, v239
	v_mov_b32_e32 v22, v240
	v_mov_b32_e32 v23, v241
	v_mov_b32_e32 v24, v134
	v_mov_b32_e32 v25, v135
	v_mov_b32_e32 v26, v136
	v_mov_b32_e32 v27, v137
	v_mov_b32_e32 v28, v138
	v_mov_b32_e32 v29, v139
	v_mov_b32_e32 v30, v140
	v_mov_b32_e32 v31, v141
	s_nop 0
	v_mov_b32_e32 v32, v244
	v_mov_b32_e32 v33, v245
	v_mov_b32_e32 v34, v246
	v_mov_b32_e32 v35, v247
	v_or_b32_e32 v127, s57, v93
	s_mov_b32 s39, 0
	v_mov_b32_e32 v106, 1.0
	v_mov_b32_e32 v131, 0
	v_readlane_b32 s62, v242, 19
	v_readlane_b32 s63, v242, 20
	v_readlane_b32 s64, v242, 21
	v_readlane_b32 s65, v242, 22
	v_readlane_b32 s66, v242, 23
	v_readlane_b32 s67, v242, 24
	v_readlane_b32 s68, v242, 25
	v_readlane_b32 s69, v242, 26
	v_readlane_b32 s70, v242, 27
	v_readlane_b32 s71, v242, 28
	v_readlane_b32 s72, v242, 29
	v_readlane_b32 s73, v242, 30
	v_readlane_b32 s74, v242, 31
	v_readlane_b32 s75, v242, 32
	s_barrier
	s_waitcnt vmcnt(10)
	v_mul_f32_e32 v36, 0xbfb8aa3b, v36
	v_exp_f32_e32 v38, v36
	s_nop 0
	v_add_f32_e32 v39, 1.0, v38
	v_add_f32_e32 v40, -1.0, v39
	v_frexp_mant_f32_e32 v41, v39
	v_cvt_f64_f32_e32 v[36:37], v39
	v_sub_f32_e32 v42, v40, v39
	v_frexp_exp_i32_f64_e32 v36, v[36:37]
	v_cmp_gt_f32_e32 vcc, s50, v41
	v_sub_f32_e32 v40, v38, v40
	v_add_f32_e32 v37, 1.0, v42
	v_subbrev_co_u32_e32 v36, vcc, 0, v36, vcc
	v_add_f32_e32 v37, v40, v37
	v_sub_u32_e32 v40, 0, v36
	v_cvt_f32_i32_e32 v36, v36
	v_ldexp_f32 v39, v39, v40
	v_ldexp_f32 v37, v37, v40
	v_add_f32_e32 v40, -1.0, v39
	v_add_f32_e32 v41, 1.0, v39
	v_add_f32_e32 v42, 1.0, v40
	v_add_f32_e32 v43, -1.0, v41
	v_sub_f32_e32 v42, v39, v42
	v_sub_f32_e32 v39, v39, v43
	v_mul_f32_e32 v43, 0x3f317218, v36
	v_add_f32_e32 v42, v37, v42
	v_add_f32_e32 v37, v37, v39
	v_fma_f32 v39, v36, s51, -v43
	v_add_f32_e32 v44, v40, v42
	v_add_f32_e32 v45, v41, v37
	v_fmac_f32_e32 v39, 0xb102e308, v36
	v_sub_f32_e32 v36, v44, v40
	v_sub_f32_e32 v40, v45, v41
	v_rcp_f32_e32 v41, v45
	v_add_f32_e32 v46, v43, v39
	v_sub_f32_e32 v37, v37, v40
	v_sub_f32_e32 v40, v46, v43
	v_sub_f32_e32 v39, v39, v40
	v_mul_f32_e32 v40, v44, v41
	v_sub_f32_e32 v36, v42, v36
	v_mul_f32_e32 v42, v45, v40
	v_fma_f32 v43, v40, v45, -v42
	v_fmac_f32_e32 v43, v40, v37
	v_add_f32_e32 v47, v42, v43
	v_sub_f32_e32 v48, v44, v47
	v_sub_f32_e32 v42, v47, v42
	v_sub_f32_e32 v44, v44, v48
	v_sub_f32_e32 v42, v42, v43
	v_sub_f32_e32 v43, v44, v47
	v_add_f32_e32 v36, v36, v43
	v_add_f32_e32 v36, v42, v36
	v_add_f32_e32 v42, v48, v36
	v_mul_f32_e32 v43, v41, v42
	v_sub_f32_e32 v44, v48, v42
	v_mul_f32_e32 v47, v45, v43
	v_add_f32_e32 v36, v36, v44
	v_add_f32_e32 v44, v40, v43
	v_fma_f32 v45, v43, v45, -v47
	v_sub_f32_e32 v40, v44, v40
	v_fmac_f32_e32 v45, v43, v37
	v_sub_f32_e32 v37, v43, v40
	v_add_f32_e32 v40, v47, v45
	v_sub_f32_e32 v43, v40, v47
	v_sub_f32_e32 v47, v42, v40
	v_sub_f32_e32 v42, v42, v47
	v_sub_f32_e32 v40, v42, v40
	v_sub_f32_e32 v43, v43, v45
	v_add_f32_e32 v36, v36, v40
	v_add_f32_e32 v36, v43, v36
	v_add_f32_e32 v36, v47, v36
	v_mul_f32_e32 v36, v41, v36
	v_add_f32_e32 v36, v37, v36
	v_add_f32_e32 v37, v44, v36
	v_mul_f32_e32 v40, v37, v37
	v_fmamk_f32 v43, v40, 0x3e9b6dac, v117
	v_sub_f32_e32 v41, v37, v44
	v_ldexp_f32 v42, v37, 1
	v_mul_f32_e32 v37, v37, v40
	v_fmaak_f32 v40, v40, v43, 0x3f2aaada
	v_mul_f32_e32 v37, v37, v40
	v_add_f32_e32 v40, v42, v37
	v_sub_f32_e32 v36, v36, v41
	v_sub_f32_e32 v41, v40, v42
	v_ldexp_f32 v36, v36, 1
	v_sub_f32_e32 v37, v37, v41
	v_add_f32_e32 v36, v36, v37
	v_add_f32_e32 v37, v40, v36
	v_sub_f32_e32 v40, v37, v40
	v_add_f32_e32 v41, v46, v37
	v_sub_f32_e32 v36, v36, v40
	v_sub_f32_e32 v40, v41, v46
	v_sub_f32_e32 v42, v41, v40
	v_sub_f32_e32 v37, v37, v40
	v_add_f32_e32 v40, v39, v36
	v_sub_f32_e32 v42, v46, v42
	v_sub_f32_e32 v43, v40, v39
	v_add_f32_e32 v37, v37, v42
	v_sub_f32_e32 v42, v40, v43
	v_sub_f32_e32 v36, v36, v43
	v_sub_f32_e32 v39, v39, v42
	v_add_f32_e32 v37, v40, v37
	v_add_f32_e32 v36, v36, v39
	v_add_f32_e32 v39, v41, v37
	v_sub_f32_e32 v40, v39, v41
	v_sub_f32_e32 v37, v37, v40
	v_add_f32_e32 v36, v36, v37
	v_add_f32_e32 v36, v39, v36
	v_cmp_neq_f32_e32 vcc, s52, v38
	s_nop 1
	v_cndmask_b32_e32 v36, v119, v36, vcc
	v_cmp_ngt_f32_e32 vcc, -1.0, v38
	s_nop 1
	v_cndmask_b32_e32 v36, v120, v36, vcc
	v_cmp_neq_f32_e32 vcc, -1.0, v38
	s_nop 1
	v_cndmask_b32_e32 v36, v121, v36, vcc
	v_cmp_lt_f32_e64 vcc, |v38|, s53
	s_nop 1
	v_cndmask_b32_e32 v36, v36, v38, vcc
	v_mul_f32_e32 v130, 0xc1000000, v36

; #define LAS __attribute__((address_space(3)))
; template <bool PASS2>
; __device__ __forceinline__ void lru_item(const Frame& F, const Args& a, int item) {
;     ...
;     for (int idx = F.tid; idx < 259 * 16; idx += 512) { const int row = idx >> 4, ch = idx & 15; const int t = t0 - 1 + row; u32x4 v = (u32x4){0u, 0u, 0u, 0u};
;         if (t >= 0 && t < SEQ) v = *(const u32x4*)(proj + (rowbase + t) * NIN + C_XB + n * 128 + 8 * ch);
;         *(LAS u32x4*)(R0 + row * AT_PITCH + 16 * ch) = v; }
.LBB0_699:
	s_mul_hi_i32 s2, s73, 0x2aaaaaab
	s_ashr_i32 s3, s2, 1
	s_lshr_b32 s8, s2, 31
	s_add_i32 s3, s3, s8
	s_mul_i32 s9, s3, 12
	s_sub_i32 s14, s73, s9
	s_ashr_i32 s9, s3, 31
	s_lshr_b32 s9, s9, 28
	s_add_i32 s9, s3, s9
	s_and_b32 s9, s9, -16
	s_ashr_i32 s2, s2, 5
	s_sub_i32 s33, s3, s9
	s_add_i32 s2, s2, s8
	s_lshl_b32 s74, s33, 8
	s_ashr_i32 s3, s2, 31
	s_lshl_b32 s44, s14, 7
	s_lshl_b64 s[8:9], s[2:3], 12
	s_ashr_i32 s45, s44, 31
	v_add_u32_e32 v8, s74, v111
	s_mov_b64 s[10:11], 0
	v_mov_b32_e32 v9, v115
	v_mov_b32_e32 v10, v113
	s_waitcnt vmcnt(0)
	s_barrier
	v_cmp_gt_u32_e64 s[10:11], 48, v144
	s_movk_i32 s3, 0x1000
	v_add_u32_e32 v9, 0x100, v8
	v_mov_b32_e32 v248, 0
	v_mov_b32_e32 v249, 0
	v_mov_b32_e32 v250, 0
	v_mov_b32_e32 v251, 0
	v_cmp_gt_u32_e32 vcc, s3, v9
	s_and_b64 vcc, vcc, s[10:11]
	s_and_saveexec_b64 s[12:13], vcc
	s_cbranch_execz .Lstg_p2a_8
	v_or_b32_e32 v6, s8, v9
	v_mov_b64_e32 v[4:5], s[34:35]
	v_mad_u64_u32 v[4:5], s[30:31], v6, s55, v[4:5]
	v_mad_i32_i24 v5, s9, v135, v5
	v_lshl_add_u64 v[4:5], s[44:45], 1, v[4:5]
	v_lshl_add_u64 v[4:5], v[4:5], 0, v[96:97]
	v_add_co_u32_e32 v4, vcc, 0x2000, v4
	s_nop 1
	v_addc_co_u32_e32 v5, vcc, 0, v5, vcc
	global_load_dwordx4 v[248:251], v[4:5], off offset:1024
.Lstg_p2a_8:
	s_or_b64 exec, exec, s[12:13]
	v_mov_b32_e32 v212, 0
	v_mov_b32_e32 v213, 0
	v_mov_b32_e32 v214, 0
	v_mov_b32_e32 v215, 0
	v_cmp_gt_u32_e32 vcc, s3, v8
	s_and_saveexec_b64 s[12:13], vcc
	s_cbranch_execz .Lstg_p2a_0
	v_or_b32_e32 v6, s8, v8
	v_mov_b64_e32 v[4:5], s[34:35]
	v_mad_u64_u32 v[4:5], s[30:31], v6, s55, v[4:5]
	v_mad_i32_i24 v5, s9, v135, v5
	v_lshl_add_u64 v[4:5], s[44:45], 1, v[4:5]
	v_lshl_add_u64 v[4:5], v[4:5], 0, v[96:97]
	v_add_co_u32_e32 v4, vcc, 0x2000, v4
	s_nop 1
	v_addc_co_u32_e32 v5, vcc, 0, v5, vcc
	global_load_dwordx4 v[212:215], v[4:5], off offset:1024
.Lstg_p2a_0:
	s_or_b64 exec, exec, s[12:13]
	v_add_u32_e32 v8, 32, v8
	v_mov_b32_e32 v216, 0
	v_mov_b32_e32 v217, 0
	v_mov_b32_e32 v218, 0
	v_mov_b32_e32 v219, 0
	v_cmp_gt_u32_e32 vcc, s3, v8
	s_and_saveexec_b64 s[12:13], vcc
	v_or_b32_e32 v6, s8, v8
	v_mov_b64_e32 v[4:5], s[34:35]
	v_mad_u64_u32 v[4:5], s[30:31], v6, s55, v[4:5]
	v_mad_i32_i24 v5, s9, v135, v5
	v_lshl_add_u64 v[4:5], s[44:45], 1, v[4:5]
	v_lshl_add_u64 v[4:5], v[4:5], 0, v[96:97]
	v_add_co_u32_e32 v4, vcc, 0x2000, v4
	s_nop 1
	v_addc_co_u32_e32 v5, vcc, 0, v5, vcc
	global_load_dwordx4 v[216:219], v[4:5], off offset:1024
	s_or_b64 exec, exec, s[12:13]
	v_add_u32_e32 v8, 32, v8
	v_mov_b32_e32 v220, 0
	v_mov_b32_e32 v221, 0
	v_mov_b32_e32 v222, 0
	v_mov_b32_e32 v223, 0
	v_cmp_gt_u32_e32 vcc, s3, v8
	s_and_saveexec_b64 s[12:13], vcc
	v_or_b32_e32 v6, s8, v8
	v_mov_b64_e32 v[4:5], s[34:35]
	v_mad_u64_u32 v[4:5], s[30:31], v6, s55, v[4:5]
	v_mad_i32_i24 v5, s9, v135, v5
	v_lshl_add_u64 v[4:5], s[44:45], 1, v[4:5]
	v_lshl_add_u64 v[4:5], v[4:5], 0, v[96:97]
	v_add_co_u32_e32 v4, vcc, 0x2000, v4
	s_nop 1
	v_addc_co_u32_e32 v5, vcc, 0, v5, vcc
	global_load_dwordx4 v[220:223], v[4:5], off offset:1024
	s_or_b64 exec, exec, s[12:13]
	v_add_u32_e32 v8, 32, v8
	v_mov_b32_e32 v224, 0
	v_mov_b32_e32 v225, 0
	v_mov_b32_e32 v226, 0
	v_mov_b32_e32 v227, 0
	v_cmp_gt_u32_e32 vcc, s3, v8
	s_and_saveexec_b64 s[12:13], vcc
	v_or_b32_e32 v6, s8, v8
	v_mov_b64_e32 v[4:5], s[34:35]
	v_mad_u64_u32 v[4:5], s[30:31], v6, s55, v[4:5]
	v_mad_i32_i24 v5, s9, v135, v5
	v_lshl_add_u64 v[4:5], s[44:45], 1, v[4:5]
	v_lshl_add_u64 v[4:5], v[4:5], 0, v[96:97]
	v_add_co_u32_e32 v4, vcc, 0x2000, v4
	s_nop 1
	v_addc_co_u32_e32 v5, vcc, 0, v5, vcc
	global_load_dwordx4 v[224:227], v[4:5], off offset:1024
	s_or_b64 exec, exec, s[12:13]
	v_add_u32_e32 v8, 32, v8
	v_mov_b32_e32 v228, 0
	v_mov_b32_e32 v229, 0
	v_mov_b32_e32 v230, 0
	v_mov_b32_e32 v231, 0
	v_cmp_gt_u32_e32 vcc, s3, v8
	s_and_saveexec_b64 s[12:13], vcc
	v_or_b32_e32 v6, s8, v8
	v_mov_b64_e32 v[4:5], s[34:35]
	v_mad_u64_u32 v[4:5], s[30:31], v6, s55, v[4:5]
	v_mad_i32_i24 v5, s9, v135, v5
	v_lshl_add_u64 v[4:5], s[44:45], 1, v[4:5]
	v_lshl_add_u64 v[4:5], v[4:5], 0, v[96:97]
	v_add_co_u32_e32 v4, vcc, 0x2000, v4
	s_nop 1
	v_addc_co_u32_e32 v5, vcc, 0, v5, vcc
	global_load_dwordx4 v[228:231], v[4:5], off offset:1024
	s_or_b64 exec, exec, s[12:13]
	v_add_u32_e32 v8, 32, v8
	v_mov_b32_e32 v232, 0
	v_mov_b32_e32 v233, 0
	v_mov_b32_e32 v234, 0
	v_mov_b32_e32 v235, 0
	v_cmp_gt_u32_e32 vcc, s3, v8
	s_and_saveexec_b64 s[12:13], vcc
	v_or_b32_e32 v6, s8, v8
	v_mov_b64_e32 v[4:5], s[34:35]
	v_mad_u64_u32 v[4:5], s[30:31], v6, s55, v[4:5]
	v_mad_i32_i24 v5, s9, v135, v5
	v_lshl_add_u64 v[4:5], s[44:45], 1, v[4:5]
	v_lshl_add_u64 v[4:5], v[4:5], 0, v[96:97]
	v_add_co_u32_e32 v4, vcc, 0x2000, v4
	s_nop 1
	v_addc_co_u32_e32 v5, vcc, 0, v5, vcc
	global_load_dwordx4 v[232:235], v[4:5], off offset:1024
	s_or_b64 exec, exec, s[12:13]
	v_add_u32_e32 v8, 32, v8
	v_mov_b32_e32 v236, 0
	v_mov_b32_e32 v237, 0
	v_mov_b32_e32 v238, 0
	v_mov_b32_e32 v239, 0
	v_cmp_gt_u32_e32 vcc, s3, v8
	s_and_saveexec_b64 s[12:13], vcc
	v_or_b32_e32 v6, s8, v8
	v_mov_b64_e32 v[4:5], s[34:35]
	v_mad_u64_u32 v[4:5], s[30:31], v6, s55, v[4:5]
; #define LAS __attribute__((address_space(3)))
; template <bool PASS2>
; __device__ __forceinline__ void lru_item(const Frame& F, const Args& a, int item) {
;     ...
;     for (int idx = F.tid; idx < 259 * 16; idx += 512) { const int row = idx >> 4, ch = idx & 15; const int t = t0 - 1 + row; u32x4 v = (u32x4){0u, 0u, 0u, 0u};
;         if (t >= 0 && t < SEQ) v = *(const u32x4*)(proj + (rowbase + t) * NIN + C_XB + n * 128 + 8 * ch);
;         *(LAS u32x4*)(R0 + row * AT_PITCH + 16 * ch) = v; }
;     {
;         f32x4 cw[4][2], cbv[2];
; #pragma unroll
;         for (int j = 0; j < 4; ++j) { cw[j][0] = *(const f32x4*)(a.conv_w + j * 1536 + n * 128 + 8 * cch); cw[j][1] = *(const f32x4*)(a.conv_w + j * 1536 + n * 128 + 8 * cch + 4); }
;         cbv[0] = *(const f32x4*)(a.conv_b + n * 128 + 8 * cch); cbv[1] = *(const f32x4*)(a.conv_b + n * 128 + 8 * cch + 4);
;         u32x4 ybv[8];
;         if (PASS2) {
; #pragma unroll
;             for (int it = 0; it < 8; ++it) ybv[it] = *(const u32x4*)(proj + (rowbase + t0 + r0 + 32 * it) * NIN + C_YB + n * 128 + 8 * cch);
;         }
;         __syncthreads();
	v_mad_i32_i24 v5, s9, v135, v5
	v_lshl_add_u64 v[4:5], s[44:45], 1, v[4:5]
	v_lshl_add_u64 v[4:5], v[4:5], 0, v[96:97]
	v_add_co_u32_e32 v4, vcc, 0x2000, v4
	s_nop 1
	v_addc_co_u32_e32 v5, vcc, 0, v5, vcc
	global_load_dwordx4 v[236:239], v[4:5], off offset:1024
	s_or_b64 exec, exec, s[12:13]
	v_add_u32_e32 v8, 32, v8
	v_mov_b32_e32 v244, 0
	v_mov_b32_e32 v245, 0
	v_mov_b32_e32 v246, 0
	v_mov_b32_e32 v247, 0
	v_cmp_gt_u32_e32 vcc, s3, v8
	s_and_saveexec_b64 s[12:13], vcc
	v_or_b32_e32 v6, s8, v8
	v_mov_b64_e32 v[4:5], s[34:35]
	v_mad_u64_u32 v[4:5], s[30:31], v6, s55, v[4:5]
	v_mad_i32_i24 v5, s9, v135, v5
	v_lshl_add_u64 v[4:5], s[44:45], 1, v[4:5]
	v_lshl_add_u64 v[4:5], v[4:5], 0, v[96:97]
	v_add_co_u32_e32 v4, vcc, 0x2000, v4
	s_nop 1
	v_addc_co_u32_e32 v5, vcc, 0, v5, vcc
	global_load_dwordx4 v[244:247], v[4:5], off offset:1024
	s_or_b64 exec, exec, s[12:13]
	s_lshl_b64 s[10:11], s[44:45], 2
	v_lshl_add_u64 v[4:5], v[98:99], 0, s[10:11]
	v_add_co_u32_e32 v8, vcc, 0x1000, v4
	s_mov_b64 s[12:13], 0x1800
	s_nop 0
	v_addc_co_u32_e32 v9, vcc, 0, v5, vcc
	global_load_dwordx4 v[76:79], v[4:5], off
	global_load_dwordx4 v[68:71], v[4:5], off offset:16
	v_lshl_add_u64 v[6:7], v[4:5], 0, s[12:13]
	global_load_dwordx4 v[36:39], v[8:9], off offset:2048
	global_load_dwordx4 v[40:43], v[6:7], off offset:16
	s_mov_b64 s[12:13], 0x3000
	v_add_co_u32_e32 v8, vcc, 0x3000, v4
	v_lshl_add_u64 v[6:7], v[4:5], 0, s[12:13]
	s_nop 0
	v_addc_co_u32_e32 v9, vcc, 0, v5, vcc
	s_mov_b64 s[12:13], 0x4800
	global_load_dwordx4 v[80:83], v[8:9], off
	global_load_dwordx4 v[72:75], v[6:7], off offset:16
	v_lshl_add_u64 v[6:7], v[4:5], 0, s[12:13]
	v_add_co_u32_e32 v4, vcc, 0x4000, v4
	s_ashr_i32 s3, s74, 31
	s_nop 0
	v_addc_co_u32_e32 v5, vcc, 0, v5, vcc
	global_load_dwordx4 v[44:47], v[4:5], off offset:2048
	global_load_dwordx4 v[48:51], v[6:7], off offset:16
	v_lshl_add_u64 v[4:5], v[100:101], 0, s[10:11]
	s_add_u32 s46, s8, s74
	global_load_dwordx4 v[52:55], v[4:5], off
	global_load_dwordx4 v[56:59], v[4:5], off offset:16
	v_or_b32_e32 v122, s46, v94
	v_mov_b64_e32 v[4:5], s[34:35]
	s_addc_u32 s47, s9, s3
	v_mad_u64_u32 v[4:5], s[8:9], v122, s55, v[4:5]
	v_mad_i32_i24 v5, s47, v135, v5
	v_lshl_add_u64 v[4:5], s[44:45], 1, v[4:5]
	v_lshl_add_u64 v[28:29], v[4:5], 0, v[96:97]
	s_movk_i32 s3, 0x3000
	v_add_co_u32_e32 v4, vcc, s3, v28
	s_mov_b32 s3, 0x8b000
	s_nop 0
	v_addc_co_u32_e32 v5, vcc, 0, v29, vcc
	v_add_co_u32_e32 v8, vcc, s3, v28
	s_mov_b32 s3, 0x113000
	s_nop 0
	v_addc_co_u32_e32 v9, vcc, 0, v29, vcc
	v_add_co_u32_e32 v12, vcc, s3, v28
	s_mov_b32 s3, 0x19b000
	s_nop 0
	v_addc_co_u32_e32 v13, vcc, 0, v29, vcc
	v_add_co_u32_e32 v16, vcc, s3, v28
	s_mov_b32 s3, 0x223000
	s_nop 0
	v_addc_co_u32_e32 v17, vcc, 0, v29, vcc
	v_add_co_u32_e32 v20, vcc, s3, v28
	s_mov_b32 s3, 0x2ab000
	s_nop 0
	v_addc_co_u32_e32 v21, vcc, 0, v29, vcc
	v_add_co_u32_e32 v24, vcc, s3, v28
	s_mov_b32 s3, 0x333000
	s_nop 0
	v_addc_co_u32_e32 v25, vcc, 0, v29, vcc
	v_add_co_u32_e32 v30, vcc, s3, v28
	s_mov_b32 s3, 0x3bb000
	s_nop 0
	v_addc_co_u32_e32 v31, vcc, 0, v29, vcc
	v_add_co_u32_e32 v32, vcc, s3, v28
	global_load_dwordx4 v[4:7], v[4:5], off
	s_nop 0
	global_load_dwordx4 v[8:11], v[8:9], off
	v_addc_co_u32_e32 v33, vcc, 0, v29, vcc
	global_load_dwordx4 v[12:15], v[12:13], off
	s_nop 0
	global_load_dwordx4 v[16:19], v[16:17], off
	s_nop 0
	global_load_dwordx4 v[20:23], v[20:21], off
	s_nop 0
	global_load_dwordx4 v[24:27], v[24:25], off
	s_nop 0
	global_load_dwordx4 v[28:31], v[30:31], off
	s_nop 0
	global_load_dwordx4 v[32:35], v[32:33], off
	s_mov_b32 s3, 0
	v_mov_b32_e32 v93, s47
	v_cmp_gt_u32_e64 s[98:99], 48, v144
	v_add_u32_e32 v240, 0x2200, v113
	s_waitcnt vmcnt(24)
	s_and_saveexec_b64 s[100:101], s[98:99]
	s_cbranch_execz .Lstg_p2a_w8
	ds_write_b128 v240, v[248:251] offset:60928
.Lstg_p2a_w8:
	s_or_b64 exec, exec, s[100:101]
	ds_write_b128 v113, v[212:215]
	ds_write_b128 v113, v[216:219] offset:8704
	s_waitcnt vmcnt(23)
	ds_write_b128 v113, v[220:223] offset:17408
	s_waitcnt vmcnt(22)
	ds_write_b128 v113, v[224:227] offset:26112
	s_waitcnt vmcnt(21)
	ds_write_b128 v113, v[228:231] offset:34816
	s_waitcnt vmcnt(20)
	ds_write_b128 v113, v[232:235] offset:43520
	s_waitcnt vmcnt(19)
	ds_write_b128 v113, v[236:239] offset:52224
	s_waitcnt vmcnt(18)
	ds_write_b128 v113, v[244:247] offset:60928
	s_waitcnt lgkmcnt(0)
	s_barrier
	s_waitcnt vmcnt(16)
	v_mov_b32_e32 v62, v70
	v_mov_b32_e32 v66, v68
	s_waitcnt vmcnt(14)
	v_mov_b32_e32 v63, v42
	v_mov_b32_e32 v42, v71
	v_mov_b32_e32 v67, v40
	v_mov_b32_e32 v40, v69
	v_mov_b32_e32 v70, v78
	v_mov_b32_e32 v71, v38
	v_mov_b32_e32 v38, v79
	s_waitcnt vmcnt(13)
	v_mov_b32_e32 v68, v82
	s_waitcnt vmcnt(12)
	v_mov_b32_e32 v60, v74
	v_mov_b32_e32 v64, v72
	v_mov_b32_e32 v72, v80
	v_mov_b32_e32 v74, v76
	v_mov_b32_e32 v76, v121
	s_waitcnt vmcnt(11)
	v_mov_b32_e32 v69, v46
	s_waitcnt vmcnt(10)
	v_mov_b32_e32 v61, v50
	v_mov_b32_e32 v50, v75
	v_mov_b32_e32 v65, v48
	v_mov_b32_e32 v48, v73
	v_mov_b32_e32 v46, v83
	v_mov_b32_e32 v73, v44
	v_mov_b32_e32 v44, v81
	v_mov_b32_e32 v75, v36
	v_mov_b32_e32 v36, v77
	v_mov_b32_e32 v77, v94

; #define LAS __attribute__((address_space(3)))
; template <bool PASS2>
; __device__ __forceinline__ void lru_item(const Frame& F, const Args& a, int item) {
;     ...
;     for (int idx = F.tid; idx < 259 * 16; idx += 512) { const int row = idx >> 4, ch = idx & 15; const int t = t0 - 1 + row; u32x4 v = (u32x4){0u, 0u, 0u, 0u};
;         if (t >= 0 && t < SEQ) v = *(const u32x4*)(proj + (rowbase + t) * NIN + C_XB + n * 128 + 8 * ch);
;         *(LAS u32x4*)(R0 + row * AT_PITCH + 16 * ch) = v; }
.LBB0_818:
	s_mul_hi_i32 s8, s78, 0x2aaaaaab
	s_ashr_i32 s9, s8, 1
	s_lshr_b32 s10, s8, 31
	s_add_i32 s9, s9, s10
	s_mul_i32 s11, s9, 12
	s_sub_i32 s29, s78, s11
	s_ashr_i32 s11, s9, 31
	s_lshr_b32 s11, s11, 28
	s_add_i32 s11, s9, s11
	s_and_b32 s11, s11, -16
	s_ashr_i32 s8, s8, 5
	s_sub_i32 s80, s9, s11
	s_add_i32 s8, s8, s10
	s_lshl_b32 s79, s80, 8
	s_ashr_i32 s9, s8, 31
	s_lshl_b32 s42, s29, 7
	s_lshl_b64 s[10:11], s[8:9], 12
	s_ashr_i32 s43, s42, 31
	v_add_u32_e32 v8, s79, v109
	s_mov_b64 s[12:13], 0
	v_mov_b32_e32 v9, v113
	v_mov_b32_e32 v10, v111
	s_barrier
	v_cmp_gt_u32_e64 s[12:13], 48, v144
	s_movk_i32 s9, 0x1000
	v_add_u32_e32 v9, 0x100, v8
	v_mov_b32_e32 v248, 0
	v_mov_b32_e32 v249, 0
	v_mov_b32_e32 v250, 0
	v_mov_b32_e32 v251, 0
	v_cmp_gt_u32_e32 vcc, s9, v9
	s_and_b64 vcc, vcc, s[12:13]
	s_and_saveexec_b64 s[14:15], vcc
	s_cbranch_execz .Lstg_p2b_8
	v_or_b32_e32 v6, s10, v9
	v_mov_b64_e32 v[4:5], s[34:35]
	v_mad_u64_u32 v[4:5], s[30:31], v6, s52, v[4:5]
	v_mad_i32_i24 v5, s11, v134, v5
	v_lshl_add_u64 v[4:5], s[42:43], 1, v[4:5]
	v_lshl_add_u64 v[4:5], v[4:5], 0, v[96:97]
	v_add_co_u32_e32 v4, vcc, 0x2000, v4
	s_nop 1
	v_addc_co_u32_e32 v5, vcc, 0, v5, vcc
	global_load_dwordx4 v[248:251], v[4:5], off offset:1024
.Lstg_p2b_8:
	s_or_b64 exec, exec, s[14:15]
	v_mov_b32_e32 v212, 0
	v_mov_b32_e32 v213, 0
	v_mov_b32_e32 v214, 0
	v_mov_b32_e32 v215, 0
	v_cmp_gt_u32_e32 vcc, s9, v8
	s_and_saveexec_b64 s[14:15], vcc
	s_cbranch_execz .Lstg_p2b_0
	v_or_b32_e32 v6, s10, v8
	v_mov_b64_e32 v[4:5], s[34:35]
	v_mad_u64_u32 v[4:5], s[30:31], v6, s52, v[4:5]
	v_mad_i32_i24 v5, s11, v134, v5
	v_lshl_add_u64 v[4:5], s[42:43], 1, v[4:5]
	v_lshl_add_u64 v[4:5], v[4:5], 0, v[96:97]
	v_add_co_u32_e32 v4, vcc, 0x2000, v4
	s_nop 1
	v_addc_co_u32_e32 v5, vcc, 0, v5, vcc
	global_load_dwordx4 v[212:215], v[4:5], off offset:1024
.Lstg_p2b_0:
	s_or_b64 exec, exec, s[14:15]
	v_add_u32_e32 v8, 32, v8
	v_mov_b32_e32 v216, 0
	v_mov_b32_e32 v217, 0
	v_mov_b32_e32 v218, 0
	v_mov_b32_e32 v219, 0
	v_cmp_gt_u32_e32 vcc, s9, v8
	s_and_saveexec_b64 s[14:15], vcc
	v_or_b32_e32 v6, s10, v8
	v_mov_b64_e32 v[4:5], s[34:35]
	v_mad_u64_u32 v[4:5], s[30:31], v6, s52, v[4:5]
	v_mad_i32_i24 v5, s11, v134, v5
	v_lshl_add_u64 v[4:5], s[42:43], 1, v[4:5]
	v_lshl_add_u64 v[4:5], v[4:5], 0, v[96:97]
	v_add_co_u32_e32 v4, vcc, 0x2000, v4
	s_nop 1
	v_addc_co_u32_e32 v5, vcc, 0, v5, vcc
	global_load_dwordx4 v[216:219], v[4:5], off offset:1024
	s_or_b64 exec, exec, s[14:15]
	v_add_u32_e32 v8, 32, v8
	v_mov_b32_e32 v220, 0
	v_mov_b32_e32 v221, 0
	v_mov_b32_e32 v222, 0
	v_mov_b32_e32 v223, 0
	v_cmp_gt_u32_e32 vcc, s9, v8
	s_and_saveexec_b64 s[14:15], vcc
	v_or_b32_e32 v6, s10, v8
	v_mov_b64_e32 v[4:5], s[34:35]
	v_mad_u64_u32 v[4:5], s[30:31], v6, s52, v[4:5]
	v_mad_i32_i24 v5, s11, v134, v5
	v_lshl_add_u64 v[4:5], s[42:43], 1, v[4:5]
	v_lshl_add_u64 v[4:5], v[4:5], 0, v[96:97]
	v_add_co_u32_e32 v4, vcc, 0x2000, v4
	s_nop 1
	v_addc_co_u32_e32 v5, vcc, 0, v5, vcc
	global_load_dwordx4 v[220:223], v[4:5], off offset:1024
	s_or_b64 exec, exec, s[14:15]
	v_add_u32_e32 v8, 32, v8
	v_mov_b32_e32 v224, 0
	v_mov_b32_e32 v225, 0
	v_mov_b32_e32 v226, 0
	v_mov_b32_e32 v227, 0
	v_cmp_gt_u32_e32 vcc, s9, v8
	s_and_saveexec_b64 s[14:15], vcc
	v_or_b32_e32 v6, s10, v8
	v_mov_b64_e32 v[4:5], s[34:35]
	v_mad_u64_u32 v[4:5], s[30:31], v6, s52, v[4:5]
	v_mad_i32_i24 v5, s11, v134, v5
	v_lshl_add_u64 v[4:5], s[42:43], 1, v[4:5]
	v_lshl_add_u64 v[4:5], v[4:5], 0, v[96:97]
	v_add_co_u32_e32 v4, vcc, 0x2000, v4
	s_nop 1
	v_addc_co_u32_e32 v5, vcc, 0, v5, vcc
	global_load_dwordx4 v[224:227], v[4:5], off offset:1024
	s_or_b64 exec, exec, s[14:15]
	v_add_u32_e32 v8, 32, v8
	v_mov_b32_e32 v228, 0
	v_mov_b32_e32 v229, 0
	v_mov_b32_e32 v230, 0
	v_mov_b32_e32 v231, 0
	v_cmp_gt_u32_e32 vcc, s9, v8
	s_and_saveexec_b64 s[14:15], vcc
	v_or_b32_e32 v6, s10, v8
	v_mov_b64_e32 v[4:5], s[34:35]
	v_mad_u64_u32 v[4:5], s[30:31], v6, s52, v[4:5]
	v_mad_i32_i24 v5, s11, v134, v5
	v_lshl_add_u64 v[4:5], s[42:43], 1, v[4:5]
	v_lshl_add_u64 v[4:5], v[4:5], 0, v[96:97]
	v_add_co_u32_e32 v4, vcc, 0x2000, v4
	s_nop 1
	v_addc_co_u32_e32 v5, vcc, 0, v5, vcc
	global_load_dwordx4 v[228:231], v[4:5], off offset:1024
	s_or_b64 exec, exec, s[14:15]
	v_add_u32_e32 v8, 32, v8
	v_mov_b32_e32 v232, 0
	v_mov_b32_e32 v233, 0
	v_mov_b32_e32 v234, 0
	v_mov_b32_e32 v235, 0
	v_cmp_gt_u32_e32 vcc, s9, v8
	s_and_saveexec_b64 s[14:15], vcc
	v_or_b32_e32 v6, s10, v8
	v_mov_b64_e32 v[4:5], s[34:35]
	v_mad_u64_u32 v[4:5], s[30:31], v6, s52, v[4:5]
	v_mad_i32_i24 v5, s11, v134, v5
	v_lshl_add_u64 v[4:5], s[42:43], 1, v[4:5]
	v_lshl_add_u64 v[4:5], v[4:5], 0, v[96:97]
	v_add_co_u32_e32 v4, vcc, 0x2000, v4
	s_nop 1
	v_addc_co_u32_e32 v5, vcc, 0, v5, vcc
	global_load_dwordx4 v[232:235], v[4:5], off offset:1024
	s_or_b64 exec, exec, s[14:15]
	v_add_u32_e32 v8, 32, v8
	v_mov_b32_e32 v236, 0
	v_mov_b32_e32 v237, 0
	v_mov_b32_e32 v238, 0
	v_mov_b32_e32 v239, 0
	v_cmp_gt_u32_e32 vcc, s9, v8
	s_and_saveexec_b64 s[14:15], vcc
	v_or_b32_e32 v6, s10, v8
	v_mov_b64_e32 v[4:5], s[34:35]
	v_mad_u64_u32 v[4:5], s[30:31], v6, s52, v[4:5]
	v_mad_i32_i24 v5, s11, v134, v5
; #define LAS __attribute__((address_space(3)))
; template <bool PASS2>
; __device__ __forceinline__ void lru_item(const Frame& F, const Args& a, int item) {
;     ...
;     for (int idx = F.tid; idx < 259 * 16; idx += 512) { const int row = idx >> 4, ch = idx & 15; const int t = t0 - 1 + row; u32x4 v = (u32x4){0u, 0u, 0u, 0u};
;         if (t >= 0 && t < SEQ) v = *(const u32x4*)(proj + (rowbase + t) * NIN + C_XB + n * 128 + 8 * ch);
;         *(LAS u32x4*)(R0 + row * AT_PITCH + 16 * ch) = v; }
;     {
;         f32x4 cw[4][2], cbv[2];
; #pragma unroll
;         for (int j = 0; j < 4; ++j) { cw[j][0] = *(const f32x4*)(a.conv_w + j * 1536 + n * 128 + 8 * cch); cw[j][1] = *(const f32x4*)(a.conv_w + j * 1536 + n * 128 + 8 * cch + 4); }
;         cbv[0] = *(const f32x4*)(a.conv_b + n * 128 + 8 * cch); cbv[1] = *(const f32x4*)(a.conv_b + n * 128 + 8 * cch + 4);
;         u32x4 ybv[8];
;         if (PASS2) {
; #pragma unroll
;             for (int it = 0; it < 8; ++it) ybv[it] = *(const u32x4*)(proj + (rowbase + t0 + r0 + 32 * it) * NIN + C_YB + n * 128 + 8 * cch);
;         }
;         __syncthreads();
	v_lshl_add_u64 v[4:5], s[42:43], 1, v[4:5]
	v_lshl_add_u64 v[4:5], v[4:5], 0, v[96:97]
	v_add_co_u32_e32 v4, vcc, 0x2000, v4
	s_nop 1
	v_addc_co_u32_e32 v5, vcc, 0, v5, vcc
	global_load_dwordx4 v[236:239], v[4:5], off offset:1024
	s_or_b64 exec, exec, s[14:15]
	v_add_u32_e32 v8, 32, v8
	v_mov_b32_e32 v244, 0
	v_mov_b32_e32 v245, 0
	v_mov_b32_e32 v246, 0
	v_mov_b32_e32 v247, 0
	v_cmp_gt_u32_e32 vcc, s9, v8
	s_and_saveexec_b64 s[14:15], vcc
	v_or_b32_e32 v6, s10, v8
	v_mov_b64_e32 v[4:5], s[34:35]
	v_mad_u64_u32 v[4:5], s[30:31], v6, s52, v[4:5]
	v_mad_i32_i24 v5, s11, v134, v5
	v_lshl_add_u64 v[4:5], s[42:43], 1, v[4:5]
	v_lshl_add_u64 v[4:5], v[4:5], 0, v[96:97]
	v_add_co_u32_e32 v4, vcc, 0x2000, v4
	s_nop 1
	v_addc_co_u32_e32 v5, vcc, 0, v5, vcc
	global_load_dwordx4 v[244:247], v[4:5], off offset:1024
	s_or_b64 exec, exec, s[14:15]
	s_lshl_b64 s[12:13], s[42:43], 2
	v_lshl_add_u64 v[12:13], v[98:99], 0, s[12:13]
	s_ashr_i32 s9, s79, 31
	v_add_co_u32_e32 v4, vcc, 0x1000, v12
	s_add_u32 s44, s10, s79
	s_mov_b64 s[14:15], 0x1800
	v_addc_co_u32_e32 v5, vcc, 0, v13, vcc
	v_or_b32_e32 v122, s44, v94
	v_mov_b64_e32 v[28:29], s[34:35]
	v_lshl_add_u64 v[8:9], v[12:13], 0, s[14:15]
	s_mov_b64 s[14:15], 0x3000
	v_add_co_u32_e32 v16, vcc, 0x3000, v12
	s_addc_u32 s45, s11, s9
	v_mad_u64_u32 v[28:29], s[10:11], v122, s52, v[28:29]
	v_lshl_add_u64 v[14:15], v[12:13], 0, s[14:15]
	v_addc_co_u32_e32 v17, vcc, 0, v13, vcc
	s_mov_b64 s[14:15], 0x4800
	v_mad_i32_i24 v29, s45, v134, v29
	global_load_dwordx4 v[76:79], v[12:13], off
	global_load_dwordx4 v[68:71], v[12:13], off offset:16
	s_nop 0
	global_load_dwordx4 v[4:7], v[4:5], off offset:2048
	s_nop 0
	global_load_dwordx4 v[8:11], v[8:9], off offset:16
	s_nop 0
	global_load_dwordx4 v[80:83], v[16:17], off
	global_load_dwordx4 v[72:75], v[14:15], off offset:16
	v_lshl_add_u64 v[16:17], v[12:13], 0, s[14:15]
	v_add_co_u32_e32 v12, vcc, 0x4000, v12
	v_lshl_add_u64 v[28:29], s[42:43], 1, v[28:29]
	s_nop 0
	v_addc_co_u32_e32 v13, vcc, 0, v13, vcc
	v_lshl_add_u64 v[28:29], v[28:29], 0, v[96:97]
	s_movk_i32 s9, 0x3000
	v_add_co_u32_e32 v30, vcc, s9, v28
	s_mov_b32 s9, 0x8b000
	s_nop 0
	v_addc_co_u32_e32 v31, vcc, 0, v29, vcc
	v_add_co_u32_e32 v32, vcc, s9, v28
	v_lshl_add_u64 v[24:25], v[100:101], 0, s[12:13]
	s_nop 0
	v_addc_co_u32_e32 v33, vcc, 0, v29, vcc
	s_mov_b32 s9, 0x113000
	global_load_dwordx4 v[12:15], v[12:13], off offset:2048
	s_nop 0
	global_load_dwordx4 v[16:19], v[16:17], off offset:16
	s_nop 0
	global_load_dwordx4 v[20:23], v[24:25], off
	s_nop 0
	global_load_dwordx4 v[24:27], v[24:25], off offset:16
	s_nop 0
	global_load_dwordx4 v[36:39], v[30:31], off
	global_load_dwordx4 v[40:43], v[32:33], off
	v_add_co_u32_e32 v30, vcc, s9, v28
	s_mov_b32 s9, 0x19b000
	s_nop 0
	v_addc_co_u32_e32 v31, vcc, 0, v29, vcc
	v_add_co_u32_e32 v32, vcc, s9, v28
	s_mov_b32 s9, 0x223000
	s_nop 0
	v_addc_co_u32_e32 v33, vcc, 0, v29, vcc
	global_load_dwordx4 v[44:47], v[30:31], off
	global_load_dwordx4 v[48:51], v[32:33], off
	v_add_co_u32_e32 v30, vcc, s9, v28
	s_mov_b32 s9, 0x2ab000
	s_nop 0
	v_addc_co_u32_e32 v31, vcc, 0, v29, vcc
	v_add_co_u32_e32 v32, vcc, s9, v28
	s_mov_b32 s9, 0x333000
	s_nop 0
	v_addc_co_u32_e32 v33, vcc, 0, v29, vcc
	global_load_dwordx4 v[52:55], v[30:31], off
	global_load_dwordx4 v[56:59], v[32:33], off
	v_add_co_u32_e32 v30, vcc, s9, v28
	s_mov_b32 s9, 0x3bb000
	s_nop 0
	v_addc_co_u32_e32 v31, vcc, 0, v29, vcc
	v_add_co_u32_e32 v28, vcc, s9, v28
	s_mov_b32 s9, 0
	s_nop 0
	v_addc_co_u32_e32 v29, vcc, 0, v29, vcc
	global_load_dwordx4 v[60:63], v[30:31], off
	global_load_dwordx4 v[64:67], v[28:29], off
	v_mov_b32_e32 v93, s45
	v_cmp_gt_u32_e64 s[98:99], 48, v144
	v_add_u32_e32 v240, 0x2200, v111
	s_waitcnt vmcnt(24)
	s_and_saveexec_b64 s[100:101], s[98:99]
	s_cbranch_execz .Lstg_p2b_w8
	ds_write_b128 v240, v[248:251] offset:60928
.Lstg_p2b_w8:
	s_or_b64 exec, exec, s[100:101]
	ds_write_b128 v111, v[212:215]
	ds_write_b128 v111, v[216:219] offset:8704
	s_waitcnt vmcnt(23)
	ds_write_b128 v111, v[220:223] offset:17408
	s_waitcnt vmcnt(22)
	ds_write_b128 v111, v[224:227] offset:26112
	s_waitcnt vmcnt(21)
	ds_write_b128 v111, v[228:231] offset:34816
	s_waitcnt vmcnt(20)
	ds_write_b128 v111, v[232:235] offset:43520
	s_waitcnt vmcnt(19)
	ds_write_b128 v111, v[236:239] offset:52224
	s_waitcnt vmcnt(18)
	ds_write_b128 v111, v[244:247] offset:60928
	s_waitcnt lgkmcnt(0)
	s_barrier
	s_waitcnt vmcnt(16)
	v_mov_b32_e32 v30, v70
	s_waitcnt vmcnt(14)
	v_mov_b32_e32 v31, v10
	s_waitcnt vmcnt(12)
	v_mov_b32_e32 v28, v74
	v_mov_b32_e32 v10, v71
	v_mov_b32_e32 v32, v72
	v_mov_b32_e32 v34, v68
	v_mov_b32_e32 v35, v8
	v_mov_b32_e32 v8, v69
	v_mov_b32_e32 v68, v82
	v_mov_b32_e32 v70, v78
	v_mov_b32_e32 v71, v6
	v_mov_b32_e32 v6, v79
	v_mov_b32_e32 v72, v80
	v_mov_b32_e32 v74, v76
	v_mov_b32_e32 v76, v115
	s_waitcnt vmcnt(11)
	v_mov_b32_e32 v69, v14
	s_waitcnt vmcnt(10)
	v_mov_b32_e32 v29, v18
	v_mov_b32_e32 v18, v75
	v_mov_b32_e32 v33, v16
	v_mov_b32_e32 v16, v73
	v_mov_b32_e32 v14, v83
	v_mov_b32_e32 v73, v12
	v_mov_b32_e32 v12, v81
	v_mov_b32_e32 v75, v4
	v_mov_b32_e32 v4, v77
	v_mov_b32_e32 v77, v94

; #define LAS __attribute__((address_space(3)))
; __global__ void __launch_bounds__(512, 2) mega_fwd(Args a) {
;     extern __shared__ __attribute__((aligned(16))) unsigned char lds_raw[];
;     Frame F; F.lds = (LAS unsigned char*)lds_raw; F.tid = threadIdx.x; F.lane = F.tid & 63; F.wave = __builtin_amdgcn_readfirstlane(F.tid >> 6); F.G = gridDim.x; F.bid = blockIdx.x;
	.amdhsa_kernel _Z8mega_fwd4Args
		.amdhsa_group_segment_fixed_size 0
		.amdhsa_private_segment_fixed_size 0
		.amdhsa_kernarg_size 472
		.amdhsa_user_sgpr_count 2
		.amdhsa_user_sgpr_dispatch_ptr 0
		.amdhsa_user_sgpr_queue_ptr 0
		.amdhsa_user_sgpr_kernarg_segment_ptr 1
		.amdhsa_user_sgpr_dispatch_id 0
		.amdhsa_user_sgpr_kernarg_preload_length 0
		.amdhsa_user_sgpr_kernarg_preload_offset 0
		.amdhsa_user_sgpr_private_segment_size 0
		.amdhsa_uses_dynamic_stack 0
		.amdhsa_enable_private_segment 0
		.amdhsa_system_sgpr_workgroup_id_x 1
		.amdhsa_system_sgpr_workgroup_id_y 0
		.amdhsa_system_sgpr_workgroup_id_z 0
		.amdhsa_system_sgpr_workgroup_info 0
		.amdhsa_system_vgpr_workitem_id 2
		.amdhsa_next_free_vgpr 256
		.amdhsa_next_free_sgpr 102
		.amdhsa_accum_offset 256
		.amdhsa_reserve_vcc 1
		.amdhsa_float_round_mode_32 0
		.amdhsa_float_round_mode_16_64 0
		.amdhsa_float_denorm_mode_32 3
		.amdhsa_float_denorm_mode_16_64 3
		.amdhsa_dx10_clamp 1
		.amdhsa_ieee_mode 1
		.amdhsa_fp16_overflow 0
		.amdhsa_tg_split 0
		.amdhsa_exception_fp_ieee_invalid_op 0
		.amdhsa_exception_fp_denorm_src 0
		.amdhsa_exception_fp_ieee_div_zero 0
		.amdhsa_exception_fp_ieee_overflow 0
		.amdhsa_exception_fp_ieee_underflow 0
		.amdhsa_exception_fp_ieee_inexact 0
		.amdhsa_exception_int_div_zero 0
	.end_amdhsa_kernel

; #define LAS __attribute__((address_space(3)))
; __global__ void __launch_bounds__(512, 2) mega_fwd(Args a) {
;     extern __shared__ __attribute__((aligned(16))) unsigned char lds_raw[];
;     Frame F; F.lds = (LAS unsigned char*)lds_raw; F.tid = threadIdx.x; F.lane = F.tid & 63; F.wave = __builtin_amdgcn_readfirstlane(F.tid >> 6); F.G = gridDim.x; F.bid = blockIdx.x;
amdhsa.kernels:
  - .agpr_count:     0
    .args:
      - .offset:         0
        .size:           216
        .value_kind:     by_value
      - .offset:         216
        .size:           4
        .value_kind:     hidden_block_count_x
      - .offset:         220
        .size:           4
        .value_kind:     hidden_block_count_y
      - .offset:         224
        .size:           4
        .value_kind:     hidden_block_count_z
      - .offset:         228
        .size:           2
        .value_kind:     hidden_group_size_x
      - .offset:         230
        .size:           2
        .value_kind:     hidden_group_size_y
      - .offset:         232
        .size:           2
        .value_kind:     hidden_group_size_z
      - .offset:         234
        .size:           2
        .value_kind:     hidden_remainder_x
      - .offset:         236
        .size:           2
        .value_kind:     hidden_remainder_y
      - .offset:         238
        .size:           2
        .value_kind:     hidden_remainder_z
      - .offset:         256
        .size:           8
        .value_kind:     hidden_global_offset_x
      - .offset:         264
        .size:           8
        .value_kind:     hidden_global_offset_y
      - .offset:         272
        .size:           8
        .value_kind:     hidden_global_offset_z
      - .offset:         280
        .size:           2
        .value_kind:     hidden_grid_dims
      - .offset:         304
        .size:           8
        .value_kind:     hidden_multigrid_sync_arg
      - .offset:         336
        .size:           4
        .value_kind:     hidden_dynamic_lds_size
    .group_segment_fixed_size: 0
    .kernarg_segment_align: 8
    .kernarg_segment_size: 472
    .language:       OpenCL C
    .language_version:
      - 2
      - 0
    .max_flat_workgroup_size: 512
    .name:           _Z8mega_fwd4Args
    .private_segment_fixed_size: 0
    .sgpr_count:     108
    .sgpr_spill_count: 82
    .symbol:         _Z8mega_fwd4Args.kd
    .uniform_work_group_size: 1
    .uses_dynamic_stack: false
    .vgpr_count:     256
    .vgpr_spill_count: 0
    .wavefront_size: 64
